# early L2 write-back by wave 1 at each grid barrier (before the XCD leader release)
# baseline (speedup 1.0000x reference)
.LBB0_126:
	s_or_b64 exec, exec, s[4:5]
	s_waitcnt vmcnt(0)
	v_mov_b32_e32 v0, v208
	s_waitcnt lgkmcnt(0)
	s_barrier
	v_cmp_eq_u32_e64 s[98:99], 64, v208
	s_and_saveexec_b64 s[100:101], s[98:99]
	s_cbranch_execz .Lewb_1
	buffer_wbl2 sc1
.Lewb_1:
	s_mov_b64 exec, s[100:101]
	s_nop 0
	v_cmp_eq_u32_e32 vcc, 0, v0
	s_and_saveexec_b64 s[0:1], vcc
	s_xor_b64 s[0:1], exec, s[0:1]
	s_cbranch_execz .LBB0_179
	s_add_i32 s3, 0, 0x21ff0
	v_mov_b32_e32 v0, s3
	s_getreg_b32 s2, hwreg(HW_REG_XCC_ID, 0, 4)
	s_waitcnt vmcnt(0) expcnt(0) lgkmcnt(0)
	ds_read_b32 v2, v0
	s_add_i32 s3, 0, 0x21ff4
	v_mov_b32_e32 v0, s3
	ds_read_b32 v0, v0
	s_and_b32 s33, s2, 15
	s_waitcnt lgkmcnt(1)
	v_cmp_ne_u32_e32 vcc, 0, v2
	s_cbranch_vccnz .LBB0_142
	s_add_u32 s2, s96, 0x352b8a00
	s_addc_u32 s3, s97, 0
	s_add_u32 s4, s96, 0x352b8c00
	s_addc_u32 s5, s97, 0
	s_add_u32 s6, s96, 0x352b8d00
	s_addc_u32 s7, s97, 0
	s_add_u32 s8, s96, 0x352b8e00
	s_addc_u32 s9, s97, 0
	s_add_u32 s10, s96, 0x352b8f00
	s_addc_u32 s11, s97, 0
	s_add_u32 s20, s96, 0x352b9000
	s_addc_u32 s21, s97, 0
	s_add_u32 s22, s96, 0x352b9100
	s_addc_u32 s23, s97, 0
	s_add_u32 s24, s96, 0x352b9200
	s_addc_u32 s25, s97, 0
	s_add_u32 s26, s96, 0x352b9300
	s_addc_u32 s27, s97, 0
	s_add_u32 s28, s96, 0x352b9400
	s_addc_u32 s29, s97, 0
	s_add_u32 s30, s96, 0x352b9500
	s_addc_u32 s31, s97, 0
	s_add_u32 s34, s96, 0x352b9600
	s_addc_u32 s35, s97, 0
	s_add_u32 s36, s96, 0x352b9700
	s_addc_u32 s37, s97, 0
	s_add_u32 s38, s96, 0x352b9800
	s_addc_u32 s39, s97, 0
	s_add_u32 s40, s96, 0x352b9900
	s_addc_u32 s41, s97, 0
	s_add_u32 s42, s96, 0x352b9a00
	s_addc_u32 s43, s97, 0
	s_add_u32 s52, s96, 0x352b9b00
	s_addc_u32 s53, s97, 0
	s_mov_b32 s44, 1
	v_mov_b32_e32 v16, 0
	s_branch .LBB0_130

.LBB0_625:
	s_waitcnt vmcnt(0)
	s_waitcnt vmcnt(0)
	v_mov_b32_e32 v0, v208
	s_waitcnt lgkmcnt(0)
	s_barrier
	v_cmp_eq_u32_e64 s[98:99], 64, v208
	s_and_saveexec_b64 s[100:101], s[98:99]
	s_cbranch_execz .Lewb_2
	buffer_wbl2 sc1
.Lewb_2:
	s_mov_b64 exec, s[100:101]
	s_nop 0
	v_cmp_eq_u32_e32 vcc, 0, v0
	s_and_saveexec_b64 s[2:3], vcc
	s_xor_b64 s[2:3], exec, s[2:3]
	s_cbranch_execz .LBB0_678
	s_add_i32 s5, 0, 0x21ff0
	v_mov_b32_e32 v0, s5
	s_getreg_b32 s4, hwreg(HW_REG_XCC_ID, 0, 4)
	s_waitcnt vmcnt(0) expcnt(0) lgkmcnt(0)
	ds_read_b32 v2, v0
	s_add_i32 s5, 0, 0x21ff4
	v_mov_b32_e32 v0, s5
	ds_read_b32 v0, v0
	s_and_b32 s33, s4, 15
	s_waitcnt lgkmcnt(1)
	v_cmp_ne_u32_e32 vcc, 0, v2
	s_cbranch_vccnz .LBB0_641
	s_add_u32 s4, s96, 0x352b8a00
	s_addc_u32 s5, s97, 0
	s_add_u32 s6, s96, 0x352b8c00
	s_addc_u32 s7, s97, 0
	s_add_u32 s8, s96, 0x352b8d00
	s_addc_u32 s9, s97, 0
	s_add_u32 s10, s96, 0x352b8e00
	s_addc_u32 s11, s97, 0
	s_add_u32 s12, s96, 0x352b8f00
	s_addc_u32 s13, s97, 0
	s_add_u32 s14, s96, 0x352b9000
	s_addc_u32 s15, s97, 0
	s_add_u32 s16, s96, 0x352b9100
	s_addc_u32 s17, s97, 0
	s_add_u32 s18, s96, 0x352b9200
	s_addc_u32 s19, s97, 0
	s_add_u32 s20, s96, 0x352b9300
	s_addc_u32 s21, s97, 0
	s_add_u32 s22, s96, 0x352b9400
	s_addc_u32 s23, s97, 0
	s_add_u32 s24, s96, 0x352b9500
	s_addc_u32 s25, s97, 0
	s_add_u32 s26, s96, 0x352b9600
	s_addc_u32 s27, s97, 0
	s_add_u32 s28, s96, 0x352b9700
	s_addc_u32 s29, s97, 0
	s_add_u32 s30, s96, 0x352b9800
	s_addc_u32 s31, s97, 0
	s_add_u32 s34, s96, 0x352b9900
	s_addc_u32 s35, s97, 0
	s_add_u32 s36, s96, 0x352b9a00
	s_addc_u32 s37, s97, 0
	s_add_u32 s38, s96, 0x352b9b00
	s_addc_u32 s39, s97, 0
	s_mov_b32 s44, 1
	v_mov_b32_e32 v16, 0
	s_branch .LBB0_629

.LBB0_773:
	s_waitcnt vmcnt(0)
	v_mov_b32_e32 v0, v208
	s_barrier
	v_cmp_eq_u32_e64 s[98:99], 64, v208
	s_and_saveexec_b64 s[100:101], s[98:99]
	s_cbranch_execz .Lewb_3
	buffer_wbl2 sc1
.Lewb_3:
	s_mov_b64 exec, s[100:101]
	s_nop 0
	v_cmp_eq_u32_e32 vcc, 0, v0
	s_and_saveexec_b64 s[2:3], vcc
	v_readlane_b32 s66, v252, 34
	v_readlane_b32 s56, v252, 58
	v_readlane_b32 s68, v252, 36
	v_readlane_b32 s74, v252, 40
	v_readlane_b32 s67, v252, 35
	v_readlane_b32 s57, v252, 59
	v_readlane_b32 s69, v252, 37
	v_readlane_b32 s75, v252, 41
	s_cbranch_execz .LBB0_825
	s_add_i32 s5, 0, 0x21ff0
	v_mov_b32_e32 v0, s5
	s_getreg_b32 s4, hwreg(HW_REG_XCC_ID, 0, 4)
	s_waitcnt vmcnt(0) expcnt(0) lgkmcnt(0)
	ds_read_b32 v2, v0
	s_add_i32 s5, 0, 0x21ff4
	v_mov_b32_e32 v0, s5
	ds_read_b32 v0, v0
	s_and_b32 s33, s4, 15
	s_waitcnt lgkmcnt(1)
	v_cmp_ne_u32_e32 vcc, 0, v2
	s_cbranch_vccnz .LBB0_789
	s_add_u32 s4, s96, 0x352b8a00
	s_addc_u32 s5, s97, 0
	s_add_u32 s6, s96, 0x352b8c00
	s_addc_u32 s7, s97, 0
	s_add_u32 s8, s96, 0x352b8d00
	s_addc_u32 s9, s97, 0
	s_add_u32 s10, s96, 0x352b8e00
	s_addc_u32 s11, s97, 0
	s_add_u32 s12, s96, 0x352b8f00
	s_addc_u32 s13, s97, 0
	s_add_u32 s14, s96, 0x352b9000
	s_addc_u32 s15, s97, 0
	s_add_u32 s16, s96, 0x352b9100
	s_addc_u32 s17, s97, 0
	s_add_u32 s18, s96, 0x352b9200
	s_addc_u32 s19, s97, 0
	s_add_u32 s20, s96, 0x352b9300
	s_addc_u32 s21, s97, 0
	s_add_u32 s22, s96, 0x352b9400
	s_addc_u32 s23, s97, 0
	s_add_u32 s24, s96, 0x352b9500
	s_addc_u32 s25, s97, 0
	s_add_u32 s26, s96, 0x352b9600
	s_addc_u32 s27, s97, 0
	s_add_u32 s28, s96, 0x352b9700
	s_addc_u32 s29, s97, 0
	s_add_u32 s30, s96, 0x352b9800
	s_addc_u32 s31, s97, 0
	s_add_u32 s34, s96, 0x352b9900
	s_addc_u32 s35, s97, 0
	s_add_u32 s36, s96, 0x352b9a00
	s_addc_u32 s37, s97, 0
	s_add_u32 s38, s96, 0x352b9b00
	s_addc_u32 s39, s97, 0
	s_mov_b32 s44, 1
	v_mov_b32_e32 v16, 0
	s_branch .LBB0_777

.LBB0_836:
	s_or_b64 exec, exec, s[6:7]
	s_waitcnt vmcnt(0)
	v_mov_b32_e32 v0, v208
	s_barrier
	v_cmp_eq_u32_e64 s[98:99], 64, v208
	s_and_saveexec_b64 s[100:101], s[98:99]
	s_cbranch_execz .Lewb_4
	buffer_wbl2 sc1

.Lewb_5:
	s_mov_b64 exec, s[100:101]
	s_nop 0
	v_cmp_eq_u32_e32 vcc, 0, v0
	s_and_saveexec_b64 s[0:1], vcc
	s_cbranch_execz .LBB0_955
	s_add_i32 s3, 0, 0x21ff0
	v_mov_b32_e32 v0, s3
	s_getreg_b32 s2, hwreg(HW_REG_XCC_ID, 0, 4)
	s_waitcnt vmcnt(0) expcnt(0) lgkmcnt(0)
	ds_read_b32 v2, v0
	s_add_i32 s3, 0, 0x21ff4
	v_mov_b32_e32 v0, s3
	ds_read_b32 v0, v0
	s_and_b32 s33, s2, 15
	s_waitcnt lgkmcnt(1)
	v_cmp_ne_u32_e32 vcc, 0, v2
	s_cbranch_vccnz .LBB0_919
	s_add_u32 s2, s96, 0x352b8a00
	s_addc_u32 s3, s97, 0
	s_add_u32 s4, s96, 0x352b8c00
	s_addc_u32 s5, s97, 0
	s_add_u32 s6, s96, 0x352b8d00
	s_addc_u32 s7, s97, 0
	s_add_u32 s8, s96, 0x352b8e00
	s_addc_u32 s9, s97, 0
	s_add_u32 s10, s96, 0x352b8f00
	s_addc_u32 s11, s97, 0
	s_add_u32 s12, s96, 0x352b9000
	s_addc_u32 s13, s97, 0
	s_add_u32 s14, s96, 0x352b9100
	s_addc_u32 s15, s97, 0
	s_add_u32 s16, s96, 0x352b9200
	s_addc_u32 s17, s97, 0
	s_add_u32 s18, s96, 0x352b9300
	s_addc_u32 s19, s97, 0
	s_add_u32 s20, s96, 0x352b9400
	s_addc_u32 s21, s97, 0
	s_add_u32 s22, s96, 0x352b9500
	s_addc_u32 s23, s97, 0
	s_add_u32 s24, s96, 0x352b9600
	s_addc_u32 s25, s97, 0
	s_add_u32 s26, s96, 0x352b9700
	s_addc_u32 s27, s97, 0
	s_add_u32 s28, s96, 0x352b9800
	s_addc_u32 s29, s97, 0
	s_add_u32 s30, s96, 0x352b9900
	s_addc_u32 s31, s97, 0
	s_add_u32 s34, s96, 0x352b9a00
	s_addc_u32 s35, s97, 0
	s_add_u32 s36, s96, 0x352b9b00
	s_addc_u32 s37, s97, 0
	s_mov_b32 s44, 1
	v_mov_b32_e32 v16, 0
	s_branch .LBB0_907

.LBB0_982:
	s_waitcnt vmcnt(0)
	v_mov_b32_e32 v0, v208
	s_waitcnt vmcnt(0) lgkmcnt(0)
	s_barrier
	v_cmp_eq_u32_e64 s[98:99], 64, v208
	s_and_saveexec_b64 s[100:101], s[98:99]
	s_cbranch_execz .Lewb_6
	buffer_wbl2 sc1
.Lewb_6:
	s_mov_b64 exec, s[100:101]
	s_nop 0
	v_cmp_eq_u32_e32 vcc, 0, v0
	s_and_saveexec_b64 s[2:3], vcc
	s_cbranch_execz .LBB0_1034
	s_add_i32 s5, 0, 0x21ff0
	v_mov_b32_e32 v0, s5
	s_getreg_b32 s4, hwreg(HW_REG_XCC_ID, 0, 4)
	s_waitcnt vmcnt(0) expcnt(0) lgkmcnt(0)
	ds_read_b32 v2, v0
	s_add_i32 s5, 0, 0x21ff4
	v_mov_b32_e32 v0, s5
	ds_read_b32 v0, v0
	s_and_b32 s33, s4, 15
	s_waitcnt lgkmcnt(1)
	v_cmp_ne_u32_e32 vcc, 0, v2
	s_cbranch_vccnz .LBB0_998
	s_add_u32 s4, s96, 0x352b8a00
	s_addc_u32 s5, s97, 0
	s_add_u32 s6, s96, 0x352b8c00
	s_addc_u32 s7, s97, 0
	s_add_u32 s8, s96, 0x352b8d00
	s_addc_u32 s9, s97, 0
	s_add_u32 s14, s96, 0x352b8e00
	s_addc_u32 s15, s97, 0
	s_add_u32 s16, s96, 0x352b8f00
	s_addc_u32 s17, s97, 0
	s_add_u32 s18, s96, 0x352b9000
	s_addc_u32 s19, s97, 0
	s_add_u32 s20, s96, 0x352b9100
	s_addc_u32 s21, s97, 0
	s_add_u32 s22, s96, 0x352b9200
	s_addc_u32 s23, s97, 0
	s_add_u32 s24, s96, 0x352b9300
	s_addc_u32 s25, s97, 0
	s_add_u32 s26, s96, 0x352b9400
	s_addc_u32 s27, s97, 0
	s_add_u32 s28, s96, 0x352b9500
	s_addc_u32 s29, s97, 0
	s_add_u32 s30, s96, 0x352b9600
	s_addc_u32 s31, s97, 0
	s_add_u32 s34, s96, 0x352b9700
	s_addc_u32 s35, s97, 0
	s_add_u32 s36, s96, 0x352b9800
	s_addc_u32 s37, s97, 0
	s_add_u32 s38, s96, 0x352b9900
	s_addc_u32 s39, s97, 0
	s_add_u32 s40, s96, 0x352b9a00
	s_addc_u32 s41, s97, 0
	s_add_u32 s42, s96, 0x352b9b00
	s_addc_u32 s43, s97, 0
	s_mov_b32 s44, 1
	v_mov_b32_e32 v16, 0
	s_branch .LBB0_986

.Lp6_done:
	v_readlane_b32 s75, v252, 46
	s_waitcnt vmcnt(0)
	v_mov_b32_e32 v0, v208
	s_barrier
	v_cmp_eq_u32_e64 s[98:99], 64, v208
	s_and_saveexec_b64 s[100:101], s[98:99]
	s_cbranch_execz .Lewb_7
	buffer_wbl2 sc1
.Lewb_7:
	s_mov_b64 exec, s[100:101]
	s_nop 0
	v_cmp_eq_u32_e32 vcc, 0, v0
	s_and_saveexec_b64 s[2:3], vcc
	s_cbranch_execz .LBB0_1094
	s_add_i32 s5, 0, 0x21ff0
	v_mov_b32_e32 v0, s5
	s_getreg_b32 s4, hwreg(HW_REG_XCC_ID, 0, 4)
	s_waitcnt vmcnt(0) expcnt(0) lgkmcnt(0)
	ds_read_b32 v2, v0
	s_add_i32 s5, 0, 0x21ff4
	v_mov_b32_e32 v0, s5
	ds_read_b32 v0, v0
	s_and_b32 s33, s4, 15
	s_waitcnt lgkmcnt(1)
	v_cmp_ne_u32_e32 vcc, 0, v2
	s_cbranch_vccnz .LBB0_1058
	s_add_u32 s4, s96, 0x352b8a00
	s_addc_u32 s5, s97, 0
	s_add_u32 s6, s96, 0x352b8c00
	s_addc_u32 s7, s97, 0
	s_add_u32 s8, s96, 0x352b8d00
	s_addc_u32 s9, s97, 0
	s_add_u32 s14, s96, 0x352b8e00
	s_addc_u32 s15, s97, 0
	s_add_u32 s16, s96, 0x352b8f00
	s_addc_u32 s17, s97, 0
	s_add_u32 s18, s96, 0x352b9000
	s_addc_u32 s19, s97, 0
	s_add_u32 s20, s96, 0x352b9100
	s_addc_u32 s21, s97, 0
	s_add_u32 s22, s96, 0x352b9200
	s_addc_u32 s23, s97, 0
	s_add_u32 s24, s96, 0x352b9300
	s_addc_u32 s25, s97, 0
	s_add_u32 s26, s96, 0x352b9400
	s_addc_u32 s27, s97, 0
	s_add_u32 s28, s96, 0x352b9500
	s_addc_u32 s29, s97, 0
	s_add_u32 s30, s96, 0x352b9600
	s_addc_u32 s31, s97, 0
	s_add_u32 s34, s96, 0x352b9700
	s_addc_u32 s35, s97, 0
	s_add_u32 s36, s96, 0x352b9800
	s_addc_u32 s37, s97, 0
	s_add_u32 s38, s96, 0x352b9900
	s_addc_u32 s39, s97, 0
	s_add_u32 s40, s96, 0x352b9a00
	s_addc_u32 s41, s97, 0
	s_add_u32 s42, s96, 0x352b9b00
	s_addc_u32 s43, s97, 0
	s_mov_b32 s51, 1
	v_mov_b32_e32 v16, 0
	s_branch .LBB0_1046

.Lewb_8:
	s_mov_b64 exec, s[100:101]
	s_nop 0
	v_cmp_eq_u32_e32 vcc, 0, v0
	s_and_saveexec_b64 s[2:3], vcc
	s_cbranch_execz .LBB0_1288
	s_add_i32 s5, 0, 0x21ff0
	v_mov_b32_e32 v0, s5
	s_getreg_b32 s4, hwreg(HW_REG_XCC_ID, 0, 4)
	s_waitcnt vmcnt(0) expcnt(0) lgkmcnt(0)
	ds_read_b32 v2, v0
	s_add_i32 s5, 0, 0x21ff4
	v_mov_b32_e32 v0, s5
	ds_read_b32 v0, v0
	s_and_b32 s33, s4, 15
	s_waitcnt lgkmcnt(1)
	v_cmp_ne_u32_e32 vcc, 0, v2
	s_cbranch_vccnz .LBB0_1252
	s_add_u32 s4, s96, 0x352b8a00
	s_addc_u32 s5, s97, 0
	s_add_u32 s6, s96, 0x352b8c00
	s_addc_u32 s7, s97, 0
	s_add_u32 s8, s96, 0x352b8d00
	s_addc_u32 s9, s97, 0
	s_add_u32 s16, s96, 0x352b8e00
	s_addc_u32 s17, s97, 0
	s_add_u32 s18, s96, 0x352b8f00
	s_addc_u32 s19, s97, 0
	s_add_u32 s20, s96, 0x352b9000
	s_addc_u32 s21, s97, 0
	s_add_u32 s22, s96, 0x352b9100
	s_addc_u32 s23, s97, 0
	s_add_u32 s24, s96, 0x352b9200
	s_addc_u32 s25, s97, 0
	s_add_u32 s26, s96, 0x352b9300
	s_addc_u32 s27, s97, 0
	s_add_u32 s28, s96, 0x352b9400
	s_addc_u32 s29, s97, 0
	s_add_u32 s30, s96, 0x352b9500
	s_addc_u32 s31, s97, 0
	s_add_u32 s34, s96, 0x352b9600
	s_addc_u32 s35, s97, 0
	s_add_u32 s36, s96, 0x352b9700
	s_addc_u32 s37, s97, 0
	s_add_u32 s38, s96, 0x352b9800
	s_addc_u32 s39, s97, 0
	s_add_u32 s40, s96, 0x352b9900
	s_addc_u32 s41, s97, 0
	s_add_u32 s42, s96, 0x352b9a00
	s_addc_u32 s43, s97, 0
	s_add_u32 s44, s96, 0x352b9b00
	s_addc_u32 s45, s97, 0
	s_mov_b32 s51, 1
	v_mov_b32_e32 v16, 0
	s_branch .LBB0_1240

.Lewb_9:
	s_mov_b64 exec, s[100:101]
	s_nop 0
	v_cmp_eq_u32_e32 vcc, 0, v0
	s_and_saveexec_b64 s[2:3], vcc
	s_cbranch_execz .LBB0_1383
	s_add_i32 s5, 0, 0x21ff0
	v_mov_b32_e32 v0, s5
	s_getreg_b32 s4, hwreg(HW_REG_XCC_ID, 0, 4)
	s_waitcnt vmcnt(0) expcnt(0) lgkmcnt(0)
	ds_read_b32 v2, v0
	s_add_i32 s5, 0, 0x21ff4
	v_mov_b32_e32 v0, s5
	ds_read_b32 v0, v0
	s_and_b32 s33, s4, 15
	s_waitcnt lgkmcnt(1)
	v_cmp_ne_u32_e32 vcc, 0, v2
	s_cbranch_vccnz .LBB0_1347
	s_add_u32 s4, s96, 0x352b8a00
	s_addc_u32 s5, s97, 0
	s_add_u32 s6, s96, 0x352b8c00
	s_addc_u32 s7, s97, 0
	s_add_u32 s8, s96, 0x352b8d00
	s_addc_u32 s9, s97, 0
	s_add_u32 s14, s96, 0x352b8e00
	s_addc_u32 s15, s97, 0
	s_add_u32 s18, s96, 0x352b8f00
	s_addc_u32 s19, s97, 0
	s_add_u32 s20, s96, 0x352b9000
	s_addc_u32 s21, s97, 0
	s_add_u32 s22, s96, 0x352b9100
	s_addc_u32 s23, s97, 0
	s_add_u32 s24, s96, 0x352b9200
	s_addc_u32 s25, s97, 0
	s_add_u32 s26, s96, 0x352b9300
	s_addc_u32 s27, s97, 0
	s_add_u32 s28, s96, 0x352b9400
	s_addc_u32 s29, s97, 0
	s_add_u32 s30, s96, 0x352b9500
	s_addc_u32 s31, s97, 0
	s_add_u32 s34, s96, 0x352b9600
	s_addc_u32 s35, s97, 0
	s_add_u32 s36, s96, 0x352b9700
	s_addc_u32 s37, s97, 0
	s_add_u32 s38, s96, 0x352b9800
	s_addc_u32 s39, s97, 0
	s_add_u32 s40, s96, 0x352b9900
	s_addc_u32 s41, s97, 0
	s_add_u32 s42, s96, 0x352b9a00
	s_addc_u32 s43, s97, 0
	s_add_u32 s44, s96, 0x352b9b00
	s_addc_u32 s45, s97, 0
	s_mov_b32 s51, 1
	v_mov_b32_e32 v16, 0
	s_branch .LBB0_1335

	.amdhsa_kernel _Z8mega_fwd6Params
		.amdhsa_group_segment_fixed_size 0
		.amdhsa_private_segment_fixed_size 0
		.amdhsa_kernarg_size 440
		.amdhsa_user_sgpr_count 2
		.amdhsa_user_sgpr_dispatch_ptr 0
		.amdhsa_user_sgpr_queue_ptr 0
		.amdhsa_user_sgpr_kernarg_segment_ptr 1
		.amdhsa_user_sgpr_dispatch_id 0
		.amdhsa_user_sgpr_kernarg_preload_length 0
		.amdhsa_user_sgpr_kernarg_preload_offset 0
		.amdhsa_user_sgpr_private_segment_size 0
		.amdhsa_uses_dynamic_stack 0
		.amdhsa_enable_private_segment 0
		.amdhsa_system_sgpr_workgroup_id_x 1
		.amdhsa_system_sgpr_workgroup_id_y 0
		.amdhsa_system_sgpr_workgroup_id_z 0
		.amdhsa_system_sgpr_workgroup_info 0
		.amdhsa_system_vgpr_workitem_id 2
		.amdhsa_next_free_vgpr 253
		.amdhsa_next_free_sgpr 102
		.amdhsa_accum_offset 256
		.amdhsa_reserve_vcc 1
		.amdhsa_float_round_mode_32 0
		.amdhsa_float_round_mode_16_64 0
		.amdhsa_float_denorm_mode_32 3
		.amdhsa_float_denorm_mode_16_64 3
		.amdhsa_dx10_clamp 1
		.amdhsa_ieee_mode 1
		.amdhsa_fp16_overflow 0
		.amdhsa_tg_split 0
		.amdhsa_exception_fp_ieee_invalid_op 0
		.amdhsa_exception_fp_denorm_src 0
		.amdhsa_exception_fp_ieee_div_zero 0
		.amdhsa_exception_fp_ieee_overflow 0
		.amdhsa_exception_fp_ieee_underflow 0
		.amdhsa_exception_fp_ieee_inexact 0
		.amdhsa_exception_int_div_zero 0
	.end_amdhsa_kernel

amdhsa.kernels:
  - .agpr_count:     0
    .args:
      - .offset:         0
        .size:           184
        .value_kind:     by_value
      - .offset:         184
        .size:           4
        .value_kind:     hidden_block_count_x
      - .offset:         188
        .size:           4
        .value_kind:     hidden_block_count_y
      - .offset:         192
        .size:           4
        .value_kind:     hidden_block_count_z
      - .offset:         196
        .size:           2
        .value_kind:     hidden_group_size_x
      - .offset:         198
        .size:           2
        .value_kind:     hidden_group_size_y
      - .offset:         200
        .size:           2
        .value_kind:     hidden_group_size_z
      - .offset:         202
        .size:           2
        .value_kind:     hidden_remainder_x
      - .offset:         204
        .size:           2
        .value_kind:     hidden_remainder_y
      - .offset:         206
        .size:           2
        .value_kind:     hidden_remainder_z
      - .offset:         224
        .size:           8
        .value_kind:     hidden_global_offset_x
      - .offset:         232
        .size:           8
        .value_kind:     hidden_global_offset_y
      - .offset:         240
        .size:           8
        .value_kind:     hidden_global_offset_z
      - .offset:         248
        .size:           2
        .value_kind:     hidden_grid_dims
      - .offset:         272
        .size:           8
        .value_kind:     hidden_multigrid_sync_arg
      - .offset:         304
        .size:           4
        .value_kind:     hidden_dynamic_lds_size
    .group_segment_fixed_size: 0
    .kernarg_segment_align: 8
    .kernarg_segment_size: 440
    .language:       OpenCL C
    .language_version:
      - 2
      - 0
    .max_flat_workgroup_size: 512
    .name:           _Z8mega_fwd6Params
    .private_segment_fixed_size: 0
    .sgpr_count:     108
    .sgpr_spill_count: 64
    .symbol:         _Z8mega_fwd6Params.kd
    .uniform_work_group_size: 1
    .uses_dynamic_stack: false
    .vgpr_count:     253
    .vgpr_spill_count: 0
    .wavefront_size: 64
